# adds to full-line MIN/UP stores: sc1 cache policy on those stores
# baseline (speedup 1.0000x reference)
; __device__ __forceinline__ unsigned cvt_pk_bf16(float lo, float hi) { unsigned r; asm volatile("v_cvt_pk_bf16_f32 %0, %1, %2" : "=v"(r) : "v"(lo), "v"(hi)); return r; }
;     __device__ __forceinline__ void operator()(const f32x4 (&acc)[2][2][4][2], const Unit& u, int wr, int wc, int fr, int fq) const {
;     ...
;                 for (int bj = 0; bj < 2; ++bj) { f32x4 v0 = acc[ai][bj][m][0] * rs, v1 = acc[ai][bj][m][1] * rs;
;                     if (mode == 2) {
; #pragma unroll
;                         for (int e = 0; e < 4; ++e) { float a = fmaxf(v0[e], 0.f), b = fmaxf(v1[e], 0.f); v0[e] = a * a; v1[e] = b * b; } }
;                     if (mode == 1 && colt >= 2048) {
; #pragma unroll
;                         for (int e = 0; e < 4; ++e) { v0[e] = __builtin_amdgcn_rcpf(1.0f + __builtin_amdgcn_exp2f(-1.4426950408889634f * v0[e])); v1[e] = __builtin_amdgcn_rcpf(1.0f + __builtin_amdgcn_exp2f(-1.4426950408889634f * v1[e])); } }
;                     u32x4 w; w.x = cvt_pk_bf16(v0[0], v0[1]); w.y = cvt_pk_bf16(v0[2], v0[3]); w.z = cvt_pk_bf16(v1[0], v1[1]); w.w = cvt_pk_bf16(v1[2], v1[3]);
;                     *(u32x4*)(rowp + bj * HALF) = w; }
.LBB0_368:
	v_cvt_pk_bf16_f32 v90, v90, v91
	v_cvt_pk_bf16_f32 v91, v86, v87
	v_cvt_pk_bf16_f32 v92, v82, v83
	v_cvt_pk_bf16_f32 v93, v88, v89
	s_mov_b32 vcc_lo, 0xff00ff00
	s_mov_b32 vcc_hi, 0xff00ff00
	v_mov_b32_dpp v222, v218 row_ror:8 row_mask:0xf bank_mask:0xf
	v_mov_b32_dpp v223, v219 row_ror:8 row_mask:0xf bank_mask:0xf
	v_mov_b32_dpp v224, v220 row_ror:8 row_mask:0xf bank_mask:0xf
	v_mov_b32_dpp v225, v221 row_ror:8 row_mask:0xf bank_mask:0xf
	v_mov_b32_dpp v242, v90 row_ror:8 row_mask:0xf bank_mask:0xf
	v_mov_b32_dpp v243, v91 row_ror:8 row_mask:0xf bank_mask:0xf
	v_mov_b32_dpp v244, v92 row_ror:8 row_mask:0xf bank_mask:0xf
	v_mov_b32_dpp v245, v93 row_ror:8 row_mask:0xf bank_mask:0xf
	v_lshl_add_u64 v[246:247], v[84:85], 0, v[214:215]
	v_lshl_add_u64 v[248:249], v[84:85], 0, v[216:217]
	v_cndmask_b32_e32 v242, v218, v242, vcc
	v_cndmask_b32_e32 v243, v219, v243, vcc
	v_cndmask_b32_e32 v244, v220, v244, vcc
	v_cndmask_b32_e32 v245, v221, v245, vcc
	v_cndmask_b32_e32 v222, v222, v90, vcc
	v_cndmask_b32_e32 v223, v223, v91, vcc
	v_cndmask_b32_e32 v224, v224, v92, vcc
	v_cndmask_b32_e32 v225, v225, v93, vcc
	global_store_dwordx4 v[246:247], v[242:245], off sc1
	global_store_dwordx4 v[248:249], v[222:225], off sc1
	s_and_b64 vcc, exec, s[42:43]
	s_nop 1
	v_cvt_f32_u32_e32 v83, v195
	v_cvt_f32_u32_e32 v82, v194
	v_fmamk_f32 v82, v83, 0x4f800000, v82
	v_fmamk_f32 v82, v82, 0x30800000, v229
	v_rsq_f32_e32 v82, v82
	s_nop 0
	v_pk_mul_f32 v[86:87], v[128:129], v[82:83] op_sel_hi:[1,0]
	v_pk_mul_f32 v[90:91], v[126:127], v[82:83] op_sel_hi:[1,0]
	v_pk_mul_f32 v[88:89], v[124:125], v[82:83] op_sel_hi:[1,0]
	v_pk_mul_f32 v[92:93], v[122:123], v[82:83] op_sel_hi:[1,0]
	s_cbranch_vccnz .LBB0_370
	v_max_f32_e32 v84, 0, v90
	v_max_f32_e32 v92, 0, v92
	v_max_f32_e32 v85, 0, v91
	v_max_f32_e32 v93, 0, v93
	v_max_f32_e32 v86, 0, v86
	v_max_f32_e32 v88, 0, v88
	v_max_f32_e32 v87, 0, v87
	v_max_f32_e32 v89, 0, v89
	v_pk_mul_f32 v[90:91], v[84:85], v[84:85]
	v_pk_mul_f32 v[86:87], v[86:87], v[86:87]
	v_pk_mul_f32 v[92:93], v[92:93], v[92:93]
	v_pk_mul_f32 v[88:89], v[88:89], v[88:89]

; __device__ __forceinline__ unsigned cvt_pk_bf16(float lo, float hi) { unsigned r; asm volatile("v_cvt_pk_bf16_f32 %0, %1, %2" : "=v"(r) : "v"(lo), "v"(hi)); return r; }
;     __device__ __forceinline__ void operator()(const f32x4 (&acc)[2][2][4][2], const Unit& u, int wr, int wc, int fr, int fq) const {
;     ...
;                 for (int bj = 0; bj < 2; ++bj) { f32x4 v0 = acc[ai][bj][m][0] * rs, v1 = acc[ai][bj][m][1] * rs;
;                     if (mode == 2) {
; #pragma unroll
;                         for (int e = 0; e < 4; ++e) { float a = fmaxf(v0[e], 0.f), b = fmaxf(v1[e], 0.f); v0[e] = a * a; v1[e] = b * b; } }
;                     if (mode == 1 && colt >= 2048) {
; #pragma unroll
;                         for (int e = 0; e < 4; ++e) { v0[e] = __builtin_amdgcn_rcpf(1.0f + __builtin_amdgcn_exp2f(-1.4426950408889634f * v0[e])); v1[e] = __builtin_amdgcn_rcpf(1.0f + __builtin_amdgcn_exp2f(-1.4426950408889634f * v1[e])); } }
;                     u32x4 w; w.x = cvt_pk_bf16(v0[0], v0[1]); w.y = cvt_pk_bf16(v0[2], v0[3]); w.z = cvt_pk_bf16(v1[0], v1[1]); w.w = cvt_pk_bf16(v1[2], v1[3]);
;                     *(u32x4*)(rowp + bj * HALF) = w; }
.LBB0_376:
	v_cvt_pk_bf16_f32 v90, v90, v91
	v_cvt_pk_bf16_f32 v91, v86, v87
	v_cvt_pk_bf16_f32 v92, v82, v83
	v_cvt_pk_bf16_f32 v93, v88, v89
	s_mov_b32 vcc_lo, 0xff00ff00
	s_mov_b32 vcc_hi, 0xff00ff00
	v_mov_b32_dpp v222, v218 row_ror:8 row_mask:0xf bank_mask:0xf
	v_mov_b32_dpp v223, v219 row_ror:8 row_mask:0xf bank_mask:0xf
	v_mov_b32_dpp v224, v220 row_ror:8 row_mask:0xf bank_mask:0xf
	v_mov_b32_dpp v225, v221 row_ror:8 row_mask:0xf bank_mask:0xf
	v_mov_b32_dpp v242, v90 row_ror:8 row_mask:0xf bank_mask:0xf
	v_mov_b32_dpp v243, v91 row_ror:8 row_mask:0xf bank_mask:0xf
	v_mov_b32_dpp v244, v92 row_ror:8 row_mask:0xf bank_mask:0xf
	v_mov_b32_dpp v245, v93 row_ror:8 row_mask:0xf bank_mask:0xf
	v_lshl_add_u64 v[246:247], v[208:209], 0, v[214:215]
	v_lshl_add_u64 v[248:249], v[208:209], 0, v[216:217]
	v_cndmask_b32_e32 v242, v218, v242, vcc
	v_cndmask_b32_e32 v243, v219, v243, vcc
	v_cndmask_b32_e32 v244, v220, v244, vcc
	v_cndmask_b32_e32 v245, v221, v245, vcc
	v_cndmask_b32_e32 v222, v222, v90, vcc
	v_cndmask_b32_e32 v223, v223, v91, vcc
	v_cndmask_b32_e32 v224, v224, v92, vcc
	v_cndmask_b32_e32 v225, v225, v93, vcc
	global_store_dwordx4 v[246:247], v[242:245], off sc1
	global_store_dwordx4 v[248:249], v[222:225], off sc1
	v_lshl_add_u64 v[208:209], v[208:209], 0, v[210:211]
	s_and_b64 vcc, exec, s[42:43]
	s_nop 1
	v_cvt_f32_u32_e32 v83, v197
	v_cvt_f32_u32_e32 v82, v196
	v_fmamk_f32 v82, v83, 0x4f800000, v82
	v_fmamk_f32 v82, v82, 0x30800000, v229
	v_rsq_f32_e32 v82, v82
	s_nop 0
	v_pk_mul_f32 v[86:87], v[110:111], v[82:83] op_sel_hi:[1,0]
	v_pk_mul_f32 v[90:91], v[108:109], v[82:83] op_sel_hi:[1,0]
	v_pk_mul_f32 v[88:89], v[106:107], v[82:83] op_sel_hi:[1,0]
	v_pk_mul_f32 v[92:93], v[104:105], v[82:83] op_sel_hi:[1,0]
	s_cbranch_vccnz .LBB0_378
	v_max_f32_e32 v84, 0, v90
	v_max_f32_e32 v92, 0, v92
	v_max_f32_e32 v85, 0, v91
	v_max_f32_e32 v93, 0, v93
	v_max_f32_e32 v86, 0, v86
	v_max_f32_e32 v88, 0, v88
	v_max_f32_e32 v87, 0, v87
	v_max_f32_e32 v89, 0, v89
	v_pk_mul_f32 v[90:91], v[84:85], v[84:85]
	v_pk_mul_f32 v[86:87], v[86:87], v[86:87]
	v_pk_mul_f32 v[92:93], v[92:93], v[92:93]
	v_pk_mul_f32 v[88:89], v[88:89], v[88:89]

; __device__ __forceinline__ unsigned cvt_pk_bf16(float lo, float hi) { unsigned r; asm volatile("v_cvt_pk_bf16_f32 %0, %1, %2" : "=v"(r) : "v"(lo), "v"(hi)); return r; }
;     __device__ __forceinline__ void operator()(const f32x4 (&acc)[2][2][4][2], const Unit& u, int wr, int wc, int fr, int fq) const {
;     ...
;                 for (int bj = 0; bj < 2; ++bj) { f32x4 v0 = acc[ai][bj][m][0] * rs, v1 = acc[ai][bj][m][1] * rs;
;                     if (mode == 2) {
; #pragma unroll
;                         for (int e = 0; e < 4; ++e) { float a = fmaxf(v0[e], 0.f), b = fmaxf(v1[e], 0.f); v0[e] = a * a; v1[e] = b * b; } }
;                     if (mode == 1 && colt >= 2048) {
; #pragma unroll
;                         for (int e = 0; e < 4; ++e) { v0[e] = __builtin_amdgcn_rcpf(1.0f + __builtin_amdgcn_exp2f(-1.4426950408889634f * v0[e])); v1[e] = __builtin_amdgcn_rcpf(1.0f + __builtin_amdgcn_exp2f(-1.4426950408889634f * v1[e])); } }
;                     u32x4 w; w.x = cvt_pk_bf16(v0[0], v0[1]); w.y = cvt_pk_bf16(v0[2], v0[3]); w.z = cvt_pk_bf16(v1[0], v1[1]); w.w = cvt_pk_bf16(v1[2], v1[3]);
;                     *(u32x4*)(rowp + bj * HALF) = w; }
.LBB0_384:
	v_cvt_pk_bf16_f32 v90, v90, v91
	v_cvt_pk_bf16_f32 v91, v86, v87
	v_cvt_pk_bf16_f32 v92, v82, v83
	v_cvt_pk_bf16_f32 v93, v88, v89
	s_mov_b32 vcc_lo, 0xff00ff00
	s_mov_b32 vcc_hi, 0xff00ff00
	v_mov_b32_dpp v222, v218 row_ror:8 row_mask:0xf bank_mask:0xf
	v_mov_b32_dpp v223, v219 row_ror:8 row_mask:0xf bank_mask:0xf
	v_mov_b32_dpp v224, v220 row_ror:8 row_mask:0xf bank_mask:0xf
	v_mov_b32_dpp v225, v221 row_ror:8 row_mask:0xf bank_mask:0xf
	v_mov_b32_dpp v242, v90 row_ror:8 row_mask:0xf bank_mask:0xf
	v_mov_b32_dpp v243, v91 row_ror:8 row_mask:0xf bank_mask:0xf
	v_mov_b32_dpp v244, v92 row_ror:8 row_mask:0xf bank_mask:0xf
	v_mov_b32_dpp v245, v93 row_ror:8 row_mask:0xf bank_mask:0xf
	v_lshl_add_u64 v[246:247], v[208:209], 0, v[214:215]
	v_lshl_add_u64 v[248:249], v[208:209], 0, v[216:217]
	v_cndmask_b32_e32 v242, v218, v242, vcc
	v_cndmask_b32_e32 v243, v219, v243, vcc
	v_cndmask_b32_e32 v244, v220, v244, vcc
	v_cndmask_b32_e32 v245, v221, v245, vcc
	v_cndmask_b32_e32 v222, v222, v90, vcc
	v_cndmask_b32_e32 v223, v223, v91, vcc
	v_cndmask_b32_e32 v224, v224, v92, vcc
	v_cndmask_b32_e32 v225, v225, v93, vcc
	global_store_dwordx4 v[246:247], v[242:245], off sc1
	global_store_dwordx4 v[248:249], v[222:225], off sc1
	v_lshl_add_u64 v[208:209], v[208:209], 0, v[210:211]
	s_and_b64 vcc, exec, s[42:43]
	s_nop 1
	v_cvt_f32_u32_e32 v83, v199
	v_cvt_f32_u32_e32 v82, v198
	v_fmamk_f32 v82, v83, 0x4f800000, v82
	v_fmamk_f32 v82, v82, 0x30800000, v229
	v_rsq_f32_e32 v82, v82
	s_nop 0
	v_pk_mul_f32 v[86:87], v[78:79], v[82:83] op_sel_hi:[1,0]
	v_pk_mul_f32 v[90:91], v[76:77], v[82:83] op_sel_hi:[1,0]
	v_pk_mul_f32 v[88:89], v[74:75], v[82:83] op_sel_hi:[1,0]
	v_pk_mul_f32 v[92:93], v[72:73], v[82:83] op_sel_hi:[1,0]
	s_cbranch_vccnz .LBB0_386
	v_max_f32_e32 v84, 0, v90
	v_max_f32_e32 v92, 0, v92
	v_max_f32_e32 v85, 0, v91
	v_max_f32_e32 v93, 0, v93
	v_max_f32_e32 v86, 0, v86
	v_max_f32_e32 v88, 0, v88
	v_max_f32_e32 v87, 0, v87
	v_max_f32_e32 v89, 0, v89
	v_pk_mul_f32 v[90:91], v[84:85], v[84:85]
	v_pk_mul_f32 v[86:87], v[86:87], v[86:87]
	v_pk_mul_f32 v[92:93], v[92:93], v[92:93]
	v_pk_mul_f32 v[88:89], v[88:89], v[88:89]

; __device__ __forceinline__ unsigned cvt_pk_bf16(float lo, float hi) { unsigned r; asm volatile("v_cvt_pk_bf16_f32 %0, %1, %2" : "=v"(r) : "v"(lo), "v"(hi)); return r; }
;     __device__ __forceinline__ void operator()(const f32x4 (&acc)[2][2][4][2], const Unit& u, int wr, int wc, int fr, int fq) const {
;     ...
;                 for (int bj = 0; bj < 2; ++bj) { f32x4 v0 = acc[ai][bj][m][0] * rs, v1 = acc[ai][bj][m][1] * rs;
;                     if (mode == 2) {
; #pragma unroll
;                         for (int e = 0; e < 4; ++e) { float a = fmaxf(v0[e], 0.f), b = fmaxf(v1[e], 0.f); v0[e] = a * a; v1[e] = b * b; } }
;                     if (mode == 1 && colt >= 2048) {
; #pragma unroll
;                         for (int e = 0; e < 4; ++e) { v0[e] = __builtin_amdgcn_rcpf(1.0f + __builtin_amdgcn_exp2f(-1.4426950408889634f * v0[e])); v1[e] = __builtin_amdgcn_rcpf(1.0f + __builtin_amdgcn_exp2f(-1.4426950408889634f * v1[e])); } }
;                     u32x4 w; w.x = cvt_pk_bf16(v0[0], v0[1]); w.y = cvt_pk_bf16(v0[2], v0[3]); w.z = cvt_pk_bf16(v1[0], v1[1]); w.w = cvt_pk_bf16(v1[2], v1[3]);
;                     *(u32x4*)(rowp + bj * HALF) = w; }
.LBB0_392:
	v_cvt_pk_bf16_f32 v90, v90, v91
	v_cvt_pk_bf16_f32 v91, v86, v87
	v_cvt_pk_bf16_f32 v92, v82, v83
	v_cvt_pk_bf16_f32 v93, v88, v89
	s_mov_b32 vcc_lo, 0xff00ff00
	s_mov_b32 vcc_hi, 0xff00ff00
	v_mov_b32_dpp v222, v218 row_ror:8 row_mask:0xf bank_mask:0xf
	v_mov_b32_dpp v223, v219 row_ror:8 row_mask:0xf bank_mask:0xf
	v_mov_b32_dpp v224, v220 row_ror:8 row_mask:0xf bank_mask:0xf
	v_mov_b32_dpp v225, v221 row_ror:8 row_mask:0xf bank_mask:0xf
	v_mov_b32_dpp v242, v90 row_ror:8 row_mask:0xf bank_mask:0xf
	v_mov_b32_dpp v243, v91 row_ror:8 row_mask:0xf bank_mask:0xf
	v_mov_b32_dpp v244, v92 row_ror:8 row_mask:0xf bank_mask:0xf
	v_mov_b32_dpp v245, v93 row_ror:8 row_mask:0xf bank_mask:0xf
	v_lshl_add_u64 v[246:247], v[208:209], 0, v[214:215]
	v_lshl_add_u64 v[248:249], v[208:209], 0, v[216:217]
	v_cndmask_b32_e32 v242, v218, v242, vcc
	v_cndmask_b32_e32 v243, v219, v243, vcc
	v_cndmask_b32_e32 v244, v220, v244, vcc
	v_cndmask_b32_e32 v245, v221, v245, vcc
	v_cndmask_b32_e32 v222, v222, v90, vcc
	v_cndmask_b32_e32 v223, v223, v91, vcc
	v_cndmask_b32_e32 v224, v224, v92, vcc
	v_cndmask_b32_e32 v225, v225, v93, vcc
	global_store_dwordx4 v[246:247], v[242:245], off sc1
	global_store_dwordx4 v[248:249], v[222:225], off sc1
	v_lshl_add_u64 v[208:209], v[208:209], 0, v[212:213]
	s_and_b64 vcc, exec, s[42:43]
	s_nop 1
	v_cvt_f32_u32_e32 v83, v201
	v_cvt_f32_u32_e32 v82, v200
	v_fmamk_f32 v82, v83, 0x4f800000, v82
	v_fmamk_f32 v82, v82, 0x30800000, v229
	v_rsq_f32_e32 v82, v82
	s_nop 0
	v_pk_mul_f32 v[86:87], v[62:63], v[82:83] op_sel_hi:[1,0]
	v_pk_mul_f32 v[90:91], v[60:61], v[82:83] op_sel_hi:[1,0]
	v_pk_mul_f32 v[88:89], v[58:59], v[82:83] op_sel_hi:[1,0]
	v_pk_mul_f32 v[92:93], v[56:57], v[82:83] op_sel_hi:[1,0]
	s_cbranch_vccnz .LBB0_394
	v_max_f32_e32 v84, 0, v90
	v_max_f32_e32 v92, 0, v92
	v_max_f32_e32 v85, 0, v91
	v_max_f32_e32 v93, 0, v93
	v_max_f32_e32 v86, 0, v86
	v_max_f32_e32 v88, 0, v88
	v_max_f32_e32 v87, 0, v87
	v_max_f32_e32 v89, 0, v89
	v_pk_mul_f32 v[90:91], v[84:85], v[84:85]
	v_pk_mul_f32 v[86:87], v[86:87], v[86:87]
	v_pk_mul_f32 v[92:93], v[92:93], v[92:93]
	v_pk_mul_f32 v[88:89], v[88:89], v[88:89]

; __device__ __forceinline__ unsigned cvt_pk_bf16(float lo, float hi) { unsigned r; asm volatile("v_cvt_pk_bf16_f32 %0, %1, %2" : "=v"(r) : "v"(lo), "v"(hi)); return r; }
;     __device__ __forceinline__ void operator()(const f32x4 (&acc)[2][2][4][2], const Unit& u, int wr, int wc, int fr, int fq) const {
;     ...
;                 for (int bj = 0; bj < 2; ++bj) { f32x4 v0 = acc[ai][bj][m][0] * rs, v1 = acc[ai][bj][m][1] * rs;
;                     if (mode == 2) {
; #pragma unroll
;                         for (int e = 0; e < 4; ++e) { float a = fmaxf(v0[e], 0.f), b = fmaxf(v1[e], 0.f); v0[e] = a * a; v1[e] = b * b; } }
;                     if (mode == 1 && colt >= 2048) {
; #pragma unroll
;                         for (int e = 0; e < 4; ++e) { v0[e] = __builtin_amdgcn_rcpf(1.0f + __builtin_amdgcn_exp2f(-1.4426950408889634f * v0[e])); v1[e] = __builtin_amdgcn_rcpf(1.0f + __builtin_amdgcn_exp2f(-1.4426950408889634f * v1[e])); } }
;                     u32x4 w; w.x = cvt_pk_bf16(v0[0], v0[1]); w.y = cvt_pk_bf16(v0[2], v0[3]); w.z = cvt_pk_bf16(v1[0], v1[1]); w.w = cvt_pk_bf16(v1[2], v1[3]);
;                     *(u32x4*)(rowp + bj * HALF) = w; }
.LBB0_400:
	v_cvt_pk_bf16_f32 v90, v90, v91
	v_cvt_pk_bf16_f32 v91, v86, v87
	v_cvt_pk_bf16_f32 v92, v82, v83
	v_cvt_pk_bf16_f32 v93, v88, v89
	s_mov_b32 vcc_lo, 0xff00ff00
	s_mov_b32 vcc_hi, 0xff00ff00
	v_mov_b32_dpp v222, v218 row_ror:8 row_mask:0xf bank_mask:0xf
	v_mov_b32_dpp v223, v219 row_ror:8 row_mask:0xf bank_mask:0xf
	v_mov_b32_dpp v224, v220 row_ror:8 row_mask:0xf bank_mask:0xf
	v_mov_b32_dpp v225, v221 row_ror:8 row_mask:0xf bank_mask:0xf
	v_mov_b32_dpp v242, v90 row_ror:8 row_mask:0xf bank_mask:0xf
	v_mov_b32_dpp v243, v91 row_ror:8 row_mask:0xf bank_mask:0xf
	v_mov_b32_dpp v244, v92 row_ror:8 row_mask:0xf bank_mask:0xf
	v_mov_b32_dpp v245, v93 row_ror:8 row_mask:0xf bank_mask:0xf
	v_lshl_add_u64 v[246:247], v[208:209], 0, v[214:215]
	v_lshl_add_u64 v[248:249], v[208:209], 0, v[216:217]
	v_cndmask_b32_e32 v242, v218, v242, vcc
	v_cndmask_b32_e32 v243, v219, v243, vcc
	v_cndmask_b32_e32 v244, v220, v244, vcc
	v_cndmask_b32_e32 v245, v221, v245, vcc
	v_cndmask_b32_e32 v222, v222, v90, vcc
	v_cndmask_b32_e32 v223, v223, v91, vcc
	v_cndmask_b32_e32 v224, v224, v92, vcc
	v_cndmask_b32_e32 v225, v225, v93, vcc
	global_store_dwordx4 v[246:247], v[242:245], off sc1
	global_store_dwordx4 v[248:249], v[222:225], off sc1
	v_lshl_add_u64 v[208:209], v[208:209], 0, v[210:211]
	s_and_b64 vcc, exec, s[42:43]
	s_nop 1
	v_cvt_f32_u32_e32 v83, v203
	v_cvt_f32_u32_e32 v82, v202
	v_fmamk_f32 v82, v83, 0x4f800000, v82
	v_fmamk_f32 v82, v82, 0x30800000, v229
	v_rsq_f32_e32 v82, v82
	s_nop 0
	v_pk_mul_f32 v[86:87], v[46:47], v[82:83] op_sel_hi:[1,0]
	v_pk_mul_f32 v[90:91], v[44:45], v[82:83] op_sel_hi:[1,0]
	v_pk_mul_f32 v[88:89], v[42:43], v[82:83] op_sel_hi:[1,0]
	v_pk_mul_f32 v[92:93], v[40:41], v[82:83] op_sel_hi:[1,0]
	s_cbranch_vccnz .LBB0_402
	v_max_f32_e32 v84, 0, v90
	v_max_f32_e32 v92, 0, v92
	v_max_f32_e32 v85, 0, v91
	v_max_f32_e32 v93, 0, v93
	v_max_f32_e32 v86, 0, v86
	v_max_f32_e32 v88, 0, v88
	v_max_f32_e32 v87, 0, v87
	v_max_f32_e32 v89, 0, v89
	v_pk_mul_f32 v[90:91], v[84:85], v[84:85]
	v_pk_mul_f32 v[86:87], v[86:87], v[86:87]
	v_pk_mul_f32 v[92:93], v[92:93], v[92:93]
	v_pk_mul_f32 v[88:89], v[88:89], v[88:89]

; __device__ __forceinline__ unsigned cvt_pk_bf16(float lo, float hi) { unsigned r; asm volatile("v_cvt_pk_bf16_f32 %0, %1, %2" : "=v"(r) : "v"(lo), "v"(hi)); return r; }
;     __device__ __forceinline__ void operator()(const f32x4 (&acc)[2][2][4][2], const Unit& u, int wr, int wc, int fr, int fq) const {
;     ...
;                 for (int bj = 0; bj < 2; ++bj) { f32x4 v0 = acc[ai][bj][m][0] * rs, v1 = acc[ai][bj][m][1] * rs;
;                     if (mode == 2) {
; #pragma unroll
;                         for (int e = 0; e < 4; ++e) { float a = fmaxf(v0[e], 0.f), b = fmaxf(v1[e], 0.f); v0[e] = a * a; v1[e] = b * b; } }
;                     if (mode == 1 && colt >= 2048) {
; #pragma unroll
;                         for (int e = 0; e < 4; ++e) { v0[e] = __builtin_amdgcn_rcpf(1.0f + __builtin_amdgcn_exp2f(-1.4426950408889634f * v0[e])); v1[e] = __builtin_amdgcn_rcpf(1.0f + __builtin_amdgcn_exp2f(-1.4426950408889634f * v1[e])); } }
;                     u32x4 w; w.x = cvt_pk_bf16(v0[0], v0[1]); w.y = cvt_pk_bf16(v0[2], v0[3]); w.z = cvt_pk_bf16(v1[0], v1[1]); w.w = cvt_pk_bf16(v1[2], v1[3]);
;                     *(u32x4*)(rowp + bj * HALF) = w; }
.LBB0_408:
	v_cvt_pk_bf16_f32 v90, v90, v91
	v_cvt_pk_bf16_f32 v91, v86, v87
	v_cvt_pk_bf16_f32 v92, v82, v83
	v_cvt_pk_bf16_f32 v93, v88, v89
	s_mov_b32 vcc_lo, 0xff00ff00
	s_mov_b32 vcc_hi, 0xff00ff00
	v_mov_b32_dpp v222, v218 row_ror:8 row_mask:0xf bank_mask:0xf
	v_mov_b32_dpp v223, v219 row_ror:8 row_mask:0xf bank_mask:0xf
	v_mov_b32_dpp v224, v220 row_ror:8 row_mask:0xf bank_mask:0xf
	v_mov_b32_dpp v225, v221 row_ror:8 row_mask:0xf bank_mask:0xf
	v_mov_b32_dpp v242, v90 row_ror:8 row_mask:0xf bank_mask:0xf
	v_mov_b32_dpp v243, v91 row_ror:8 row_mask:0xf bank_mask:0xf
	v_mov_b32_dpp v244, v92 row_ror:8 row_mask:0xf bank_mask:0xf
	v_mov_b32_dpp v245, v93 row_ror:8 row_mask:0xf bank_mask:0xf
	v_lshl_add_u64 v[246:247], v[208:209], 0, v[214:215]
	v_lshl_add_u64 v[248:249], v[208:209], 0, v[216:217]
	v_cndmask_b32_e32 v242, v218, v242, vcc
	v_cndmask_b32_e32 v243, v219, v243, vcc
	v_cndmask_b32_e32 v244, v220, v244, vcc
	v_cndmask_b32_e32 v245, v221, v245, vcc
	v_cndmask_b32_e32 v222, v222, v90, vcc
	v_cndmask_b32_e32 v223, v223, v91, vcc
	v_cndmask_b32_e32 v224, v224, v92, vcc
	v_cndmask_b32_e32 v225, v225, v93, vcc
	global_store_dwordx4 v[246:247], v[242:245], off sc1
	global_store_dwordx4 v[248:249], v[222:225], off sc1
	v_lshl_add_u64 v[208:209], v[208:209], 0, v[210:211]
	s_and_b64 vcc, exec, s[42:43]
	s_nop 1
	v_cvt_f32_u32_e32 v83, v205
	v_cvt_f32_u32_e32 v82, v204
	v_fmamk_f32 v82, v83, 0x4f800000, v82
	v_fmamk_f32 v82, v82, 0x30800000, v229
	v_rsq_f32_e32 v82, v82
	s_nop 0
	v_pk_mul_f32 v[86:87], v[30:31], v[82:83] op_sel_hi:[1,0]
	v_pk_mul_f32 v[90:91], v[28:29], v[82:83] op_sel_hi:[1,0]
	v_pk_mul_f32 v[88:89], v[26:27], v[82:83] op_sel_hi:[1,0]
	v_pk_mul_f32 v[92:93], v[24:25], v[82:83] op_sel_hi:[1,0]
	s_cbranch_vccnz .LBB0_410
	v_max_f32_e32 v84, 0, v90
	v_max_f32_e32 v92, 0, v92
	v_max_f32_e32 v85, 0, v91
	v_max_f32_e32 v93, 0, v93
	v_max_f32_e32 v86, 0, v86
	v_max_f32_e32 v88, 0, v88
	v_max_f32_e32 v87, 0, v87
	v_max_f32_e32 v89, 0, v89
	v_pk_mul_f32 v[90:91], v[84:85], v[84:85]
	v_pk_mul_f32 v[86:87], v[86:87], v[86:87]
	v_pk_mul_f32 v[92:93], v[92:93], v[92:93]
	v_pk_mul_f32 v[88:89], v[88:89], v[88:89]

; __device__ __forceinline__ unsigned cvt_pk_bf16(float lo, float hi) { unsigned r; asm volatile("v_cvt_pk_bf16_f32 %0, %1, %2" : "=v"(r) : "v"(lo), "v"(hi)); return r; }
;     __device__ __forceinline__ void operator()(const f32x4 (&acc)[2][2][4][2], const Unit& u, int wr, int wc, int fr, int fq) const {
;     ...
;                 for (int bj = 0; bj < 2; ++bj) { f32x4 v0 = acc[ai][bj][m][0] * rs, v1 = acc[ai][bj][m][1] * rs;
;                     if (mode == 2) {
; #pragma unroll
;                         for (int e = 0; e < 4; ++e) { float a = fmaxf(v0[e], 0.f), b = fmaxf(v1[e], 0.f); v0[e] = a * a; v1[e] = b * b; } }
;                     if (mode == 1 && colt >= 2048) {
; #pragma unroll
;                         for (int e = 0; e < 4; ++e) { v0[e] = __builtin_amdgcn_rcpf(1.0f + __builtin_amdgcn_exp2f(-1.4426950408889634f * v0[e])); v1[e] = __builtin_amdgcn_rcpf(1.0f + __builtin_amdgcn_exp2f(-1.4426950408889634f * v1[e])); } }
;                     u32x4 w; w.x = cvt_pk_bf16(v0[0], v0[1]); w.y = cvt_pk_bf16(v0[2], v0[3]); w.z = cvt_pk_bf16(v1[0], v1[1]); w.w = cvt_pk_bf16(v1[2], v1[3]);
;                     *(u32x4*)(rowp + bj * HALF) = w; }
.LBB0_416:
	v_cvt_pk_bf16_f32 v90, v90, v91
	v_cvt_pk_bf16_f32 v91, v86, v87
	v_cvt_pk_bf16_f32 v92, v82, v83
	v_cvt_pk_bf16_f32 v93, v88, v89
	s_mov_b32 vcc_lo, 0xff00ff00
	s_mov_b32 vcc_hi, 0xff00ff00
	v_mov_b32_dpp v222, v218 row_ror:8 row_mask:0xf bank_mask:0xf
	v_mov_b32_dpp v223, v219 row_ror:8 row_mask:0xf bank_mask:0xf
	v_mov_b32_dpp v224, v220 row_ror:8 row_mask:0xf bank_mask:0xf
	v_mov_b32_dpp v225, v221 row_ror:8 row_mask:0xf bank_mask:0xf
	v_mov_b32_dpp v242, v90 row_ror:8 row_mask:0xf bank_mask:0xf
	v_mov_b32_dpp v243, v91 row_ror:8 row_mask:0xf bank_mask:0xf
	v_mov_b32_dpp v244, v92 row_ror:8 row_mask:0xf bank_mask:0xf
	v_mov_b32_dpp v245, v93 row_ror:8 row_mask:0xf bank_mask:0xf
	v_lshl_add_u64 v[246:247], v[208:209], 0, v[214:215]
	v_lshl_add_u64 v[248:249], v[208:209], 0, v[216:217]
	v_cndmask_b32_e32 v242, v218, v242, vcc
	v_cndmask_b32_e32 v243, v219, v243, vcc
	v_cndmask_b32_e32 v244, v220, v244, vcc
	v_cndmask_b32_e32 v245, v221, v245, vcc
	v_cndmask_b32_e32 v222, v222, v90, vcc
	v_cndmask_b32_e32 v223, v223, v91, vcc
	v_cndmask_b32_e32 v224, v224, v92, vcc
	v_cndmask_b32_e32 v225, v225, v93, vcc
	global_store_dwordx4 v[246:247], v[242:245], off sc1
	global_store_dwordx4 v[248:249], v[222:225], off sc1
	v_lshl_add_u64 v[208:209], v[208:209], 0, v[210:211]
	s_and_b64 vcc, exec, s[42:43]
	s_nop 1
	v_cvt_f32_u32_e32 v81, v207
	v_cvt_f32_u32_e32 v80, v206
	v_fmamk_f32 v80, v81, 0x4f800000, v80
	v_fmamk_f32 v80, v80, 0x30800000, v229
	v_rsq_f32_e32 v80, v80
	s_nop 0
	v_pk_mul_f32 v[84:85], v[14:15], v[80:81] op_sel_hi:[1,0]
	v_pk_mul_f32 v[88:89], v[12:13], v[80:81] op_sel_hi:[1,0]
	v_pk_mul_f32 v[86:87], v[10:11], v[80:81] op_sel_hi:[1,0]
	v_pk_mul_f32 v[90:91], v[8:9], v[80:81] op_sel_hi:[1,0]
	s_cbranch_vccnz .LBB0_418
	v_max_f32_e32 v82, 0, v88
	v_max_f32_e32 v90, 0, v90
	v_max_f32_e32 v83, 0, v89
	v_max_f32_e32 v91, 0, v91
	v_max_f32_e32 v84, 0, v84
	v_max_f32_e32 v86, 0, v86
	v_max_f32_e32 v85, 0, v85
	v_max_f32_e32 v87, 0, v87
	v_pk_mul_f32 v[88:89], v[82:83], v[82:83]
	v_pk_mul_f32 v[84:85], v[84:85], v[84:85]
	v_pk_mul_f32 v[90:91], v[90:91], v[90:91]
	v_pk_mul_f32 v[86:87], v[86:87], v[86:87]

; __device__ __forceinline__ unsigned cvt_pk_bf16(float lo, float hi) { unsigned r; asm volatile("v_cvt_pk_bf16_f32 %0, %1, %2" : "=v"(r) : "v"(lo), "v"(hi)); return r; }
;     __device__ __forceinline__ void operator()(const f32x4 (&acc)[2][2][4][2], const Unit& u, int wr, int wc, int fr, int fq) const {
;     ...
;                 for (int bj = 0; bj < 2; ++bj) { f32x4 v0 = acc[ai][bj][m][0] * rs, v1 = acc[ai][bj][m][1] * rs;
;                     if (mode == 2) {
; #pragma unroll
;                         for (int e = 0; e < 4; ++e) { float a = fmaxf(v0[e], 0.f), b = fmaxf(v1[e], 0.f); v0[e] = a * a; v1[e] = b * b; } }
;                     if (mode == 1 && colt >= 2048) {
; #pragma unroll
;                         for (int e = 0; e < 4; ++e) { v0[e] = __builtin_amdgcn_rcpf(1.0f + __builtin_amdgcn_exp2f(-1.4426950408889634f * v0[e])); v1[e] = __builtin_amdgcn_rcpf(1.0f + __builtin_amdgcn_exp2f(-1.4426950408889634f * v1[e])); } }
;                     u32x4 w; w.x = cvt_pk_bf16(v0[0], v0[1]); w.y = cvt_pk_bf16(v0[2], v0[3]); w.z = cvt_pk_bf16(v1[0], v1[1]); w.w = cvt_pk_bf16(v1[2], v1[3]);
;                     *(u32x4*)(rowp + bj * HALF) = w; }
.LBB0_424:
	v_cvt_pk_bf16_f32 v88, v88, v89
	v_cvt_pk_bf16_f32 v89, v86, v87
	v_cvt_pk_bf16_f32 v90, v80, v81
	v_cvt_pk_bf16_f32 v91, v84, v85
	s_mov_b32 vcc_lo, 0xff00ff00
	s_mov_b32 vcc_hi, 0xff00ff00
	v_mov_b32_dpp v222, v218 row_ror:8 row_mask:0xf bank_mask:0xf
	v_mov_b32_dpp v223, v219 row_ror:8 row_mask:0xf bank_mask:0xf
	v_mov_b32_dpp v224, v220 row_ror:8 row_mask:0xf bank_mask:0xf
	v_mov_b32_dpp v225, v221 row_ror:8 row_mask:0xf bank_mask:0xf
	v_mov_b32_dpp v242, v88 row_ror:8 row_mask:0xf bank_mask:0xf
	v_mov_b32_dpp v243, v89 row_ror:8 row_mask:0xf bank_mask:0xf
	v_mov_b32_dpp v244, v90 row_ror:8 row_mask:0xf bank_mask:0xf
	v_mov_b32_dpp v245, v91 row_ror:8 row_mask:0xf bank_mask:0xf
	v_lshl_add_u64 v[246:247], v[208:209], 0, v[214:215]
	v_lshl_add_u64 v[248:249], v[208:209], 0, v[216:217]
	v_cndmask_b32_e32 v242, v218, v242, vcc
	v_cndmask_b32_e32 v243, v219, v243, vcc
	v_cndmask_b32_e32 v244, v220, v244, vcc
	v_cndmask_b32_e32 v245, v221, v245, vcc
	v_cndmask_b32_e32 v222, v222, v88, vcc
	v_cndmask_b32_e32 v223, v223, v89, vcc
	v_cndmask_b32_e32 v224, v224, v90, vcc
	v_cndmask_b32_e32 v225, v225, v91, vcc
	global_store_dwordx4 v[246:247], v[242:245], off sc1
	global_store_dwordx4 v[248:249], v[222:225], off sc1
	s_branch .LBB0_359
